# MLA main loop rewritten: 3-stage LDS ring, QK/softmax/PV of the two query sub-blocks software-pipelined (bf16 MFMA, f32 softmax as baseline)
# speedup vs baseline: 1.0148x; 1.0148x over previous
.LBB0_251:
	s_or_b64 exec, exec, s[2:3]
	v_add_f32_e32 v100, 0, v114
	v_add_f32_e32 v80, 0, v80
	v_add_f32_e32 v100, v115, v100
	v_add_f32_e32 v80, v81, v80
	v_add_f32_e32 v100, v116, v100
	v_add_f32_e32 v80, v82, v80
	v_add_f32_e32 v100, v117, v100
	v_add_f32_e32 v80, v83, v80
	v_add_f32_e32 v100, v118, v100
	v_add_f32_e32 v80, v84, v80
	v_add_f32_e32 v100, v119, v100
	v_add_f32_e32 v80, v85, v80
	v_add_f32_e32 v100, v120, v100
	v_add_f32_e32 v80, v86, v80
	v_add_f32_e32 v100, v121, v100
	v_add_f32_e32 v80, v87, v80
	v_add_f32_e32 v100, v122, v100
	v_add_f32_e32 v80, v88, v80
	v_add_f32_e32 v100, v123, v100
	v_add_f32_e32 v80, v89, v80
	v_add_f32_e32 v100, v124, v100
	v_add_f32_e32 v80, v90, v80
	v_add_f32_e32 v100, v125, v100
	v_add_f32_e32 v80, v91, v80
	v_add_f32_e32 v100, v126, v100
	v_add_f32_e32 v80, v92, v80
	v_add_f32_e32 v100, v127, v100
	v_add_f32_e32 v80, v93, v80
	v_add_f32_e32 v100, v176, v100
	v_add_f32_e32 v80, v94, v80
	v_add_f32_e32 v100, v177, v100
	v_add_f32_e32 v80, v95, v80
	v_add_f32_e32 v100, v178, v100
	v_add_f32_e32 v64, v64, v80
	v_add_f32_e32 v100, v179, v100
	v_add_f32_e32 v64, v65, v64
	v_add_f32_e32 v100, v180, v100
	v_add_f32_e32 v64, v66, v64
	v_add_f32_e32 v100, v181, v100
	v_add_f32_e32 v64, v67, v64
	v_add_f32_e32 v100, v182, v100
	v_add_f32_e32 v64, v68, v64
	v_add_f32_e32 v100, v183, v100
	v_add_f32_e32 v64, v69, v64
	v_add_f32_e32 v100, v184, v100
	v_add_f32_e32 v64, v70, v64
	v_add_f32_e32 v100, v185, v100
	v_add_f32_e32 v64, v71, v64
	v_add_f32_e32 v100, v186, v100
	v_add_f32_e32 v64, v72, v64
	v_add_f32_e32 v100, v187, v100
	v_add_f32_e32 v64, v73, v64
	v_add_f32_e32 v100, v200, v100
	v_add_f32_e32 v64, v74, v64
	v_add_f32_e32 v100, v201, v100
	v_add_f32_e32 v64, v75, v64
	v_add_f32_e32 v100, v202, v100
	v_add_f32_e32 v64, v76, v64
	v_add_f32_e32 v100, v104, v100
	v_add_f32_e32 v64, v77, v64
	v_add_f32_e32 v100, v105, v100
	v_add_f32_e32 v64, v78, v64
	v_mul_u32_u24_e32 v220, 0xd0, v109
	v_mul_u32_u24_e32 v221, 0x90, v109
	v_add_f32_e32 v109, v106, v100
	v_add_f32_e32 v111, v79, v64
	v_pk_add_f32 v[202:203], v[108:109], 0 op_sel_hi:[1,0]
	v_pk_add_f32 v[200:201], v[110:111], 0 op_sel_hi:[1,0]
	v_add_u32_e32 v64, 0x8800, v113
	s_mov_b32 s9, 2
	s_waitcnt vmcnt(0)
	ds_write2_b64 v64, v[96:97], v[98:99] offset0:128 offset1:130
	s_mov_b32 s3, 0
	s_mov_b32 s2, 0x6000
	s_movk_i32 s0, 0x100
	v_lshl_add_u64 v[184:185], v[194:195], 0, s[2:3]
	v_lshl_add_u64 v[180:181], v[196:197], 0, s[2:3]
	v_lshl_add_u64 v[176:177], v[198:199], 0, s[0:1]
	global_load_dwordx4 v[184:187], v[184:185], off
	global_load_dwordx4 v[180:183], v[180:181], off
	global_load_dwordx4 v[176:179], v[176:177], off
	s_movk_i32 s2, 0x5800
	v_add3_u32 v220, v220, v188, s2
	s_movk_i32 s2, 0x3400
	v_add3_u32 v221, v221, v188, s2
	v_add_u32_e32 v238, 0xe000, v219
	v_add_u32_e32 v219, 0x3000, v219
	v_xor_b32_e32 v64, 0x80000000, v202
	v_mov_b32_e32 v65, v64
	v_mov_b32_e32 v66, v64
	v_mov_b32_e32 v67, v64
	v_mov_b32_e32 v68, v64
	v_mov_b32_e32 v69, v64
	v_mov_b32_e32 v70, v64
	v_mov_b32_e32 v71, v64
	v_mov_b32_e32 v72, v64
	v_mov_b32_e32 v73, v64
	v_mov_b32_e32 v74, v64
	v_mov_b32_e32 v75, v64
	v_mov_b32_e32 v76, v64
	v_mov_b32_e32 v77, v64
	v_mov_b32_e32 v78, v64
	v_mov_b32_e32 v79, v64
	v_mov_b32_e32 v96, 0xff800000
	v_mov_b32_e32 v97, 0xff800000
	v_mov_b32_e32 v98, 0xff800000
	v_mov_b32_e32 v99, 0xff800000
	v_mov_b32_e32 v100, 0xff800000
	v_mov_b32_e32 v101, 0xff800000
	v_mov_b32_e32 v102, 0xff800000
	v_mov_b32_e32 v103, 0xff800000
	v_mov_b32_e32 v104, 0xff800000
	v_mov_b32_e32 v105, 0xff800000
	v_mov_b32_e32 v106, 0xff800000
	v_mov_b32_e32 v107, 0xff800000
	v_mov_b32_e32 v108, 0xff800000
	v_mov_b32_e32 v109, 0xff800000
	v_mov_b32_e32 v110, 0xff800000
	v_mov_b32_e32 v111, 0xff800000
	v_mov_b32_e32 v80, 0xff800000
	v_mov_b32_e32 v81, 0xff800000
	v_mov_b32_e32 v82, 0xff800000
	v_mov_b32_e32 v83, 0xff800000
	v_mov_b32_e32 v84, 0xff800000
	v_mov_b32_e32 v85, 0xff800000
	v_mov_b32_e32 v86, 0xff800000
	v_mov_b32_e32 v87, 0xff800000
	v_mov_b32_e32 v88, 0xff800000
	v_mov_b32_e32 v89, 0xff800000
	v_mov_b32_e32 v90, 0xff800000
	v_mov_b32_e32 v91, 0xff800000
	v_mov_b32_e32 v92, 0xff800000
	v_mov_b32_e32 v93, 0xff800000
	v_mov_b32_e32 v94, 0xff800000
	v_mov_b32_e32 v95, 0xff800000
	s_mov_b32 s10, 1
	s_mov_b32 s3, 0
	s_waitcnt vmcnt(0)
	ds_write_b128 v216, v[184:187] offset:45056
	s_and_saveexec_b64 vcc, s[4:5]
	ds_write_b128 v217, v[180:183] offset:45056
	s_mov_b64 exec, vcc
	ds_write2_b64 v238, v[176:177], v[178:179] offset0:128 offset1:130
	s_nop 3
	s_mov_b32 s2, 0x9000
	s_movk_i32 s0, 0x180
	v_lshl_add_u64 v[184:185], v[194:195], 0, s[2:3]
	v_lshl_add_u64 v[180:181], v[196:197], 0, s[2:3]
	v_lshl_add_u64 v[176:177], v[198:199], 0, s[0:1]
	global_load_dwordx4 v[184:187], v[184:185], off
	global_load_dwordx4 v[180:183], v[180:181], off
	global_load_dwordx4 v[176:179], v[176:177], off
	s_waitcnt lgkmcnt(0)
	s_barrier
	ds_read_b128 v[222:225], v220
	ds_read_b128 v[226:229], v220 offset:6656
	ds_read_b128 v[230:233], v220 offset:32
	ds_read_b128 v[234:237], v220 offset:6688
.Lmla_loop:
	s_waitcnt lgkmcnt(3)
	v_mfma_f32_32x32x16_bf16 v[112:127], v[222:225], v[128:131], v[64:79]
	ds_read_b128 v[222:225], v220 offset:64
	v_exp_f32_e32 v80, v80
	v_exp_f32_e32 v81, v81
	v_exp_f32_e32 v82, v82
	v_exp_f32_e32 v83, v83
	v_exp_f32_e32 v84, v84
	s_waitcnt lgkmcnt(3)
	v_mfma_f32_32x32x16_bf16 v[64:79], v[226:229], v[128:131], v[64:79]
	ds_read_b128 v[226:229], v220 offset:6720
	v_exp_f32_e32 v85, v85
	v_exp_f32_e32 v86, v86
	v_exp_f32_e32 v87, v87
	v_exp_f32_e32 v88, v88
	v_add_f32_e32 v201, v201, v80
	s_waitcnt lgkmcnt(3)
	v_mfma_f32_32x32x16_bf16 v[112:127], v[230:233], v[132:135], v[112:127]
	ds_read_b128 v[230:233], v220 offset:96
	v_exp_f32_e32 v89, v89
	v_add_f32_e32 v201, v201, v81
	v_exp_f32_e32 v90, v90
	v_add_f32_e32 v201, v201, v82
	v_exp_f32_e32 v91, v91
	v_add_f32_e32 v201, v201, v83
	s_waitcnt lgkmcnt(3)
	v_mfma_f32_32x32x16_bf16 v[64:79], v[234:237], v[132:135], v[64:79]
	ds_read_b128 v[234:237], v220 offset:6752
	v_exp_f32_e32 v92, v92
	v_add_f32_e32 v201, v201, v84
	v_exp_f32_e32 v93, v93
	v_add_f32_e32 v201, v201, v85
	v_exp_f32_e32 v94, v94
	v_add_f32_e32 v201, v201, v86
	s_waitcnt lgkmcnt(3)
	v_mfma_f32_32x32x16_bf16 v[112:127], v[222:225], v[136:139], v[112:127]
	ds_read_b128 v[222:225], v220 offset:128
	v_exp_f32_e32 v95, v95
	v_add_f32_e32 v201, v201, v87
	v_cvt_pk_bf16_f32 v80, v80, v81
	v_cvt_pk_bf16_f32 v81, v82, v83
	v_cvt_pk_bf16_f32 v82, v84, v85
	v_cvt_pk_bf16_f32 v83, v86, v87
	v_exp_f32_e32 v96, v96
	v_add_f32_e32 v201, v201, v88
	s_waitcnt lgkmcnt(3)
	v_mfma_f32_32x32x16_bf16 v[64:79], v[226:229], v[136:139], v[64:79]
	ds_read_b128 v[226:229], v220 offset:6784
	v_exp_f32_e32 v97, v97
	v_add_f32_e32 v201, v201, v89
	v_exp_f32_e32 v98, v98
	v_add_f32_e32 v201, v201, v90
	v_exp_f32_e32 v99, v99
	v_add_f32_e32 v201, v201, v91
	s_waitcnt lgkmcnt(3)
	v_mfma_f32_32x32x16_bf16 v[112:127], v[230:233], v[140:143], v[112:127]
	ds_read_b128 v[230:233], v220 offset:160
	v_exp_f32_e32 v100, v100
	v_add_f32_e32 v201, v201, v92
	v_exp_f32_e32 v101, v101
	v_add_f32_e32 v201, v201, v93
	v_exp_f32_e32 v102, v102
	v_add_f32_e32 v201, v201, v94
	s_waitcnt lgkmcnt(3)
	v_mfma_f32_32x32x16_bf16 v[64:79], v[234:237], v[140:143], v[64:79]
	ds_read_b128 v[234:237], v220 offset:6816
	v_exp_f32_e32 v103, v103
	v_add_f32_e32 v201, v201, v95
	v_cvt_pk_bf16_f32 v88, v88, v89
	v_cvt_pk_bf16_f32 v89, v90, v91
	v_cvt_pk_bf16_f32 v90, v92, v93
	v_cvt_pk_bf16_f32 v91, v94, v95
	v_exp_f32_e32 v104, v104
	v_add_f32_e32 v201, v201, v96
	s_waitcnt lgkmcnt(3)
	v_mfma_f32_32x32x16_bf16 v[112:127], v[222:225], v[144:147], v[112:127]
	ds_read_b128 v[222:225], v221 offset:64
	v_exp_f32_e32 v105, v105
	v_add_f32_e32 v201, v201, v97
	v_exp_f32_e32 v106, v106
	v_add_f32_e32 v201, v201, v98
	v_exp_f32_e32 v107, v107
	v_add_f32_e32 v201, v201, v99
	s_waitcnt lgkmcnt(3)
	v_mfma_f32_32x32x16_bf16 v[64:79], v[226:229], v[144:147], v[64:79]
	ds_read_b128 v[226:229], v221 offset:4672
	v_exp_f32_e32 v108, v108
	v_add_f32_e32 v201, v201, v100
	v_exp_f32_e32 v109, v109
	v_add_f32_e32 v201, v201, v101
	v_exp_f32_e32 v110, v110
	v_add_f32_e32 v201, v201, v102
	s_waitcnt lgkmcnt(3)
	v_mfma_f32_32x32x16_bf16 v[112:127], v[230:233], v[148:151], v[112:127]
	ds_read_b128 v[230:233], v221 offset:96
	v_exp_f32_e32 v111, v111
	v_add_f32_e32 v201, v201, v103
	v_cvt_pk_bf16_f32 v96, v96, v97
	v_cvt_pk_bf16_f32 v97, v98, v99
	v_cvt_pk_bf16_f32 v98, v100, v101
	v_cvt_pk_bf16_f32 v99, v102, v103
	v_add_f32_e32 v201, v201, v104
	v_add_f32_e32 v201, v201, v105
	v_add_f32_e32 v201, v201, v106
	s_waitcnt lgkmcnt(3)
	v_mfma_f32_32x32x16_bf16 v[64:79], v[234:237], v[148:151], v[64:79]
	ds_read_b128 v[234:237], v221 offset:4704
	v_add_f32_e32 v201, v201, v107
	v_add_f32_e32 v201, v201, v108
	v_add_f32_e32 v201, v201, v109
	v_add_f32_e32 v201, v201, v110
	v_add_f32_e32 v201, v201, v111
	v_cvt_pk_bf16_f32 v104, v104, v105
	v_cvt_pk_bf16_f32 v105, v106, v107
	v_cvt_pk_bf16_f32 v106, v108, v109
	v_cvt_pk_bf16_f32 v107, v110, v111
	s_waitcnt lgkmcnt(3)
	v_mfma_f32_32x32x16_bf16 v[0:15], v[222:225], v[80:83], v[0:15]
	ds_read_b128 v[222:225], v221
	s_waitcnt lgkmcnt(3)
	v_mfma_f32_32x32x16_bf16 v[16:31], v[226:229], v[80:83], v[16:31]
	ds_read_b128 v[226:229], v221 offset:4608
	s_waitcnt lgkmcnt(3)
	v_mfma_f32_32x32x16_bf16 v[0:15], v[230:233], v[88:91], v[0:15]
	ds_read_b128 v[230:233], v221 offset:32
	v_xor_b32_e32 v80, 0x80000000, v200
	v_mov_b32_e32 v81, v80
	v_mov_b32_e32 v82, v80
	v_mov_b32_e32 v83, v80
	v_mov_b32_e32 v84, v80
	v_mov_b32_e32 v85, v80
	v_mov_b32_e32 v86, v80
	v_mov_b32_e32 v87, v80
	v_mov_b32_e32 v92, v80
	v_mov_b32_e32 v93, v80
	s_waitcnt lgkmcnt(3)
	v_mfma_f32_32x32x16_bf16 v[16:31], v[234:237], v[88:91], v[16:31]
	ds_read_b128 v[234:237], v221 offset:4640
	v_mov_b32_e32 v94, v80
	v_mov_b32_e32 v95, v80
	v_max3_f32 v238, v112, v113, v114
	v_max3_f32 v238, v238, v115, v116
	v_max3_f32 v238, v238, v117, v118
	v_max3_f32 v238, v238, v119, v120
	v_max3_f32 v239, v64, v65, v66
	v_max3_f32 v238, v238, v121, v122
	v_max3_f32 v239, v239, v67, v68
	v_max3_f32 v238, v238, v123, v124
	s_waitcnt lgkmcnt(3)
	v_mfma_f32_32x32x16_bf16 v[0:15], v[222:225], v[96:99], v[0:15]
	ds_read_b128 v[222:225], v220
	v_mov_b32_e32 v88, v80
	v_mov_b32_e32 v89, v80
	v_mov_b32_e32 v90, v80
	v_mov_b32_e32 v91, v80
	v_max3_f32 v239, v239, v69, v70
	v_max3_f32 v238, v238, v125, v126
	v_max3_f32 v239, v239, v71, v72
	v_max_f32_e32 v238, v238, v127
	v_max3_f32 v239, v239, v73, v74
	v_max3_f32 v239, v239, v75, v76
	s_waitcnt lgkmcnt(3)
	v_mfma_f32_32x32x16_bf16 v[16:31], v[226:229], v[96:99], v[16:31]
	ds_read_b128 v[226:229], v220 offset:6656
	s_mov_b32 s2, 0x5800
	s_cmp_eq_u32 s10, 0
	s_cselect_b32 s2, 0xffff5000, s2
	v_add_u32_e32 v221, s2, v221
	v_max3_f32 v239, v239, v77, v78
	v_max_f32_e32 v239, v239, v79
	v_max_f32_e32 v238, v238, v239
	ds_bpermute_b32 v188, v218, v238
	s_waitcnt lgkmcnt(4)
	v_mfma_f32_32x32x16_bf16 v[0:15], v[230:233], v[104:107], v[0:15]
	ds_read_b128 v[230:233], v220 offset:32
	s_waitcnt lgkmcnt(4)
	v_mfma_f32_32x32x16_bf16 v[16:31], v[234:237], v[104:107], v[16:31]
	ds_read_b128 v[234:237], v220 offset:6688
	s_barrier
	s_waitcnt lgkmcnt(2)
	v_max_f32_e32 v238, v238, v188
	v_cmp_lt_f32_e32 vcc, 0x41000000, v238
	s_cbranch_vccz .Lmla_skipA
	s_nop 15
	v_max_f32_e32 v238, 0, v238
	v_exp_f32_e64 v239, -v238
	v_add_f32_e32 v202, v202, v238
	s_nop 0
	v_mul_f32_e32 v203, v203, v239
	v_mul_f32_e32 v32, v32, v239
	v_mul_f32_e32 v33, v33, v239
	v_mul_f32_e32 v34, v34, v239
	v_mul_f32_e32 v35, v35, v239
	v_mul_f32_e32 v36, v36, v239
	v_mul_f32_e32 v37, v37, v239
	v_mul_f32_e32 v38, v38, v239
	v_mul_f32_e32 v39, v39, v239
	v_mul_f32_e32 v40, v40, v239
	v_mul_f32_e32 v41, v41, v239
	v_mul_f32_e32 v42, v42, v239
	v_mul_f32_e32 v43, v43, v239
	v_mul_f32_e32 v44, v44, v239
	v_mul_f32_e32 v45, v45, v239
	v_mul_f32_e32 v46, v46, v239
	v_mul_f32_e32 v47, v47, v239
	v_mul_f32_e32 v48, v48, v239
	v_mul_f32_e32 v49, v49, v239
	v_mul_f32_e32 v50, v50, v239
	v_mul_f32_e32 v51, v51, v239
	v_mul_f32_e32 v52, v52, v239
	v_mul_f32_e32 v53, v53, v239
	v_mul_f32_e32 v54, v54, v239
	v_mul_f32_e32 v55, v55, v239
	v_mul_f32_e32 v56, v56, v239
	v_mul_f32_e32 v57, v57, v239
	v_mul_f32_e32 v58, v58, v239
	v_mul_f32_e32 v59, v59, v239
	v_mul_f32_e32 v60, v60, v239
	v_mul_f32_e32 v61, v61, v239
	v_mul_f32_e32 v62, v62, v239
	v_mul_f32_e32 v63, v63, v239
	v_sub_f32_e32 v112, v112, v238
	v_sub_f32_e32 v113, v113, v238
	v_sub_f32_e32 v114, v114, v238
	v_sub_f32_e32 v115, v115, v238
	v_sub_f32_e32 v116, v116, v238
	v_sub_f32_e32 v117, v117, v238
	v_sub_f32_e32 v118, v118, v238
	v_sub_f32_e32 v119, v119, v238
	v_sub_f32_e32 v120, v120, v238
	v_sub_f32_e32 v121, v121, v238
	v_sub_f32_e32 v122, v122, v238
	v_sub_f32_e32 v123, v123, v238
	v_sub_f32_e32 v124, v124, v238
	v_sub_f32_e32 v125, v125, v238
	v_sub_f32_e32 v126, v126, v238
	v_sub_f32_e32 v127, v127, v238
	v_sub_f32_e32 v64, v64, v238
	v_sub_f32_e32 v65, v65, v238
	v_sub_f32_e32 v66, v66, v238
	v_sub_f32_e32 v67, v67, v238
	v_sub_f32_e32 v68, v68, v238
	v_sub_f32_e32 v69, v69, v238
	v_sub_f32_e32 v70, v70, v238
	v_sub_f32_e32 v71, v71, v238
	v_sub_f32_e32 v72, v72, v238
	v_sub_f32_e32 v73, v73, v238
	v_sub_f32_e32 v74, v74, v238
	v_sub_f32_e32 v75, v75, v238
	v_sub_f32_e32 v76, v76, v238
	v_sub_f32_e32 v77, v77, v238
	v_sub_f32_e32 v78, v78, v238
	v_sub_f32_e32 v79, v79, v238
.Lmla_skipA:
	v_mfma_f32_32x32x16_bf16 v[96:111], v[222:225], v[152:155], v[80:95]
	ds_read_b128 v[222:225], v220 offset:64
	s_waitcnt vmcnt(0)
	ds_write_b128 v216, v[184:187]
	s_and_saveexec_b64 vcc, s[4:5]
	ds_write_b128 v217, v[180:183]
	s_mov_b64 exec, vcc
	ds_write2_b64 v219, v[176:177], v[178:179] offset0:128 offset1:130
	v_exp_f32_e32 v64, v64
	v_exp_f32_e32 v65, v65
	v_exp_f32_e32 v66, v66
	v_mfma_f32_32x32x16_bf16 v[80:95], v[226:229], v[152:155], v[80:95]
	ds_read_b128 v[226:229], v220 offset:6720
	v_exp_f32_e32 v67, v67
	v_exp_f32_e32 v68, v68
	v_exp_f32_e32 v69, v69
	v_exp_f32_e32 v70, v70
	v_exp_f32_e32 v71, v71
	s_waitcnt lgkmcnt(6)
	v_mfma_f32_32x32x16_bf16 v[96:111], v[230:233], v[156:159], v[96:111]
	ds_read_b128 v[230:233], v220 offset:96
	s_add_i32 s0, s9, 2
	s_min_u32 s0, s0, 0x7f
	s_mul_i32 s2, s0, 0x3000
	s_lshl_b32 s0, s0, 7
	v_lshl_add_u64 v[184:185], v[194:195], 0, s[2:3]
	v_lshl_add_u64 v[180:181], v[196:197], 0, s[2:3]
	v_lshl_add_u64 v[176:177], v[198:199], 0, s[0:1]
	global_load_dwordx4 v[184:187], v[184:185], off
	global_load_dwordx4 v[180:183], v[180:181], off
	global_load_dwordx4 v[176:179], v[176:177], off
	v_exp_f32_e32 v72, v72
	v_add_f32_e32 v203, v203, v64
	s_waitcnt lgkmcnt(6)
	v_mfma_f32_32x32x16_bf16 v[80:95], v[234:237], v[156:159], v[80:95]
	ds_read_b128 v[234:237], v220 offset:6752
	s_mov_b32 s2, 0x5800
	s_cmp_eq_u32 s10, 0
	s_cselect_b32 s2, 0xffff5000, s2
	v_add_u32_e32 v216, s2, v216
	v_add_u32_e32 v217, s2, v217
	v_add_u32_e32 v219, s2, v219
	s_mov_b32 s3, 0
	v_exp_f32_e32 v73, v73
	v_add_f32_e32 v203, v203, v65
	v_exp_f32_e32 v74, v74
	v_add_f32_e32 v203, v203, v66
	s_waitcnt lgkmcnt(6)
	v_mfma_f32_32x32x16_bf16 v[96:111], v[222:225], v[160:163], v[96:111]
	ds_read_b128 v[222:225], v220 offset:128
	v_exp_f32_e32 v75, v75
	v_add_f32_e32 v203, v203, v67
	v_exp_f32_e32 v76, v76
	v_add_f32_e32 v203, v203, v68
	v_exp_f32_e32 v77, v77
	v_add_f32_e32 v203, v203, v69
	s_waitcnt lgkmcnt(3)
	v_mfma_f32_32x32x16_bf16 v[80:95], v[226:229], v[160:163], v[80:95]
	ds_read_b128 v[226:229], v220 offset:6784
	v_exp_f32_e32 v78, v78
	v_add_f32_e32 v203, v203, v70
	v_exp_f32_e32 v79, v79
	v_add_f32_e32 v203, v203, v71
	v_cvt_pk_bf16_f32 v64, v64, v65
	v_cvt_pk_bf16_f32 v65, v66, v67
	v_cvt_pk_bf16_f32 v66, v68, v69
	v_cvt_pk_bf16_f32 v67, v70, v71
	s_waitcnt lgkmcnt(3)
	v_mfma_f32_32x32x16_bf16 v[96:111], v[230:233], v[164:167], v[96:111]
	ds_read_b128 v[230:233], v220 offset:160
	v_exp_f32_e32 v112, v112
	v_add_f32_e32 v203, v203, v72
	v_exp_f32_e32 v113, v113
	v_add_f32_e32 v203, v203, v73
	v_exp_f32_e32 v114, v114
	v_add_f32_e32 v203, v203, v74
	s_waitcnt lgkmcnt(3)
	v_mfma_f32_32x32x16_bf16 v[80:95], v[234:237], v[164:167], v[80:95]
	ds_read_b128 v[234:237], v220 offset:6816
	v_exp_f32_e32 v115, v115
	v_add_f32_e32 v203, v203, v75
	v_exp_f32_e32 v116, v116
	v_add_f32_e32 v203, v203, v76
	v_exp_f32_e32 v117, v117
	v_add_f32_e32 v203, v203, v77
	s_waitcnt lgkmcnt(3)
	v_mfma_f32_32x32x16_bf16 v[96:111], v[222:225], v[168:171], v[96:111]
	ds_read_b128 v[222:225], v221 offset:64
	v_exp_f32_e32 v118, v118
	v_add_f32_e32 v203, v203, v78
	v_exp_f32_e32 v119, v119
	v_add_f32_e32 v203, v203, v79
	v_cvt_pk_bf16_f32 v72, v72, v73
	v_cvt_pk_bf16_f32 v73, v74, v75
	v_cvt_pk_bf16_f32 v74, v76, v77
	v_cvt_pk_bf16_f32 v75, v78, v79
	s_waitcnt lgkmcnt(3)
	v_mfma_f32_32x32x16_bf16 v[80:95], v[226:229], v[168:171], v[80:95]
	ds_read_b128 v[226:229], v221 offset:4672
	s_mov_b32 s2, 0x5800
	s_cmp_eq_u32 s10, 2
	s_cselect_b32 s2, 0xffff5000, s2
	v_add_u32_e32 v220, s2, v220
	s_mov_b32 s3, 0
	v_exp_f32_e32 v120, v120
	v_add_f32_e32 v203, v203, v112
	v_exp_f32_e32 v121, v121
	v_add_f32_e32 v203, v203, v113
	v_exp_f32_e32 v122, v122
	v_add_f32_e32 v203, v203, v114
	s_waitcnt lgkmcnt(3)
	v_mfma_f32_32x32x16_bf16 v[96:111], v[230:233], v[172:175], v[96:111]
	ds_read_b128 v[230:233], v221 offset:96
	v_exp_f32_e32 v123, v123
	v_add_f32_e32 v203, v203, v115
	v_exp_f32_e32 v124, v124
	v_add_f32_e32 v203, v203, v116
	v_exp_f32_e32 v125, v125
	v_add_f32_e32 v203, v203, v117
	s_waitcnt lgkmcnt(3)
	v_mfma_f32_32x32x16_bf16 v[80:95], v[234:237], v[172:175], v[80:95]
	ds_read_b128 v[234:237], v221 offset:4704
	v_exp_f32_e32 v126, v126
	v_add_f32_e32 v203, v203, v118
	v_exp_f32_e32 v127, v127
	v_add_f32_e32 v203, v203, v119
	v_cvt_pk_bf16_f32 v112, v112, v113
	v_cvt_pk_bf16_f32 v113, v114, v115
	v_cvt_pk_bf16_f32 v114, v116, v117
	v_cvt_pk_bf16_f32 v115, v118, v119
	s_waitcnt lgkmcnt(3)
	v_mfma_f32_32x32x16_bf16 v[32:47], v[222:225], v[64:67], v[32:47]
	ds_read_b128 v[222:225], v221
	v_add_f32_e32 v203, v203, v120
	v_add_f32_e32 v203, v203, v121
	v_add_f32_e32 v203, v203, v122
	v_add_f32_e32 v203, v203, v123
	v_add_f32_e32 v203, v203, v124
	v_add_f32_e32 v203, v203, v125
	v_add_f32_e32 v203, v203, v126
	v_add_f32_e32 v203, v203, v127
	v_cvt_pk_bf16_f32 v120, v120, v121
	v_cvt_pk_bf16_f32 v121, v122, v123
	s_waitcnt lgkmcnt(3)
	v_mfma_f32_32x32x16_bf16 v[48:63], v[226:229], v[64:67], v[48:63]
	ds_read_b128 v[226:229], v221 offset:4608
	v_cvt_pk_bf16_f32 v122, v124, v125
	v_cvt_pk_bf16_f32 v123, v126, v127
	s_waitcnt lgkmcnt(3)
	v_mfma_f32_32x32x16_bf16 v[32:47], v[230:233], v[72:75], v[32:47]
	ds_read_b128 v[230:233], v221 offset:32
	v_max3_f32 v238, v96, v97, v98
	v_max3_f32 v238, v238, v99, v100
	v_max3_f32 v238, v238, v101, v102
	v_max3_f32 v238, v238, v103, v104
	s_waitcnt lgkmcnt(3)
	v_mfma_f32_32x32x16_bf16 v[48:63], v[234:237], v[72:75], v[48:63]
	ds_read_b128 v[234:237], v221 offset:4640
	v_max3_f32 v239, v80, v81, v82
	v_max3_f32 v238, v238, v105, v106
	v_max3_f32 v239, v239, v83, v84
	v_max3_f32 v238, v238, v107, v108
	v_max3_f32 v239, v239, v85, v86
	v_max3_f32 v238, v238, v109, v110
	v_max3_f32 v239, v239, v87, v88
	v_max_f32_e32 v238, v238, v111
	v_max3_f32 v239, v239, v89, v90
	v_max3_f32 v239, v239, v91, v92
	s_waitcnt lgkmcnt(3)
	v_mfma_f32_32x32x16_bf16 v[32:47], v[222:225], v[112:115], v[32:47]
	ds_read_b128 v[222:225], v220
	v_max3_f32 v239, v239, v93, v94
	v_max_f32_e32 v239, v239, v95
	v_max_f32_e32 v238, v238, v239
	ds_bpermute_b32 v188, v218, v238
	v_xor_b32_e32 v64, 0x80000000, v202
	v_mov_b32_e32 v65, v64
	v_mov_b32_e32 v66, v64
	v_mov_b32_e32 v67, v64
	v_mov_b32_e32 v68, v64
	v_mov_b32_e32 v69, v64
	v_mov_b32_e32 v70, v64
	s_waitcnt lgkmcnt(4)
	v_mfma_f32_32x32x16_bf16 v[48:63], v[226:229], v[112:115], v[48:63]
	ds_read_b128 v[226:229], v220 offset:6656
	v_mov_b32_e32 v71, v64
	v_mov_b32_e32 v72, v64
	v_mov_b32_e32 v73, v64
	v_mov_b32_e32 v74, v64
	v_mov_b32_e32 v75, v64
	v_mov_b32_e32 v76, v64
	v_mov_b32_e32 v77, v64
	v_mov_b32_e32 v78, v64
	v_mov_b32_e32 v79, v64
	s_waitcnt lgkmcnt(4)
	v_mfma_f32_32x32x16_bf16 v[32:47], v[230:233], v[120:123], v[32:47]
	ds_read_b128 v[230:233], v220 offset:32
	s_waitcnt lgkmcnt(2)
	v_max_f32_e32 v238, v238, v188
	v_cmp_lt_f32_e32 vcc, 0x41000000, v238
	s_cbranch_vccz .Lmla_skipB
	s_nop 15
	v_max_f32_e32 v238, 0, v238
	v_exp_f32_e64 v239, -v238
	v_add_f32_e32 v200, v200, v238
	s_nop 0
	v_mul_f32_e32 v201, v201, v239
	v_mul_f32_e32 v0, v0, v239
	v_mul_f32_e32 v1, v1, v239
	v_mul_f32_e32 v2, v2, v239
	v_mul_f32_e32 v3, v3, v239
	v_mul_f32_e32 v4, v4, v239
	v_mul_f32_e32 v5, v5, v239
	v_mul_f32_e32 v6, v6, v239
	v_mul_f32_e32 v7, v7, v239
	v_mul_f32_e32 v8, v8, v239
	v_mul_f32_e32 v9, v9, v239
	v_mul_f32_e32 v10, v10, v239
	v_mul_f32_e32 v11, v11, v239
	v_mul_f32_e32 v12, v12, v239
	v_mul_f32_e32 v13, v13, v239
	v_mul_f32_e32 v14, v14, v239
	v_mul_f32_e32 v15, v15, v239
	v_mul_f32_e32 v16, v16, v239
	v_mul_f32_e32 v17, v17, v239
	v_mul_f32_e32 v18, v18, v239
	v_mul_f32_e32 v19, v19, v239
	v_mul_f32_e32 v20, v20, v239
	v_mul_f32_e32 v21, v21, v239
	v_mul_f32_e32 v22, v22, v239
	v_mul_f32_e32 v23, v23, v239
	v_mul_f32_e32 v24, v24, v239
	v_mul_f32_e32 v25, v25, v239
	v_mul_f32_e32 v26, v26, v239
	v_mul_f32_e32 v27, v27, v239
	v_mul_f32_e32 v28, v28, v239
	v_mul_f32_e32 v29, v29, v239
	v_mul_f32_e32 v30, v30, v239
	v_mul_f32_e32 v31, v31, v239
	v_sub_f32_e32 v96, v96, v238
	v_sub_f32_e32 v97, v97, v238
	v_sub_f32_e32 v98, v98, v238
	v_sub_f32_e32 v99, v99, v238
	v_sub_f32_e32 v100, v100, v238
	v_sub_f32_e32 v101, v101, v238
	v_sub_f32_e32 v102, v102, v238
	v_sub_f32_e32 v103, v103, v238
	v_sub_f32_e32 v104, v104, v238
	v_sub_f32_e32 v105, v105, v238
	v_sub_f32_e32 v106, v106, v238
	v_sub_f32_e32 v107, v107, v238
	v_sub_f32_e32 v108, v108, v238
	v_sub_f32_e32 v109, v109, v238
	v_sub_f32_e32 v110, v110, v238
	v_sub_f32_e32 v111, v111, v238
	v_sub_f32_e32 v80, v80, v238
	v_sub_f32_e32 v81, v81, v238
	v_sub_f32_e32 v82, v82, v238
	v_sub_f32_e32 v83, v83, v238
	v_sub_f32_e32 v84, v84, v238
	v_sub_f32_e32 v85, v85, v238
	v_sub_f32_e32 v86, v86, v238
	v_sub_f32_e32 v87, v87, v238
	v_sub_f32_e32 v88, v88, v238
	v_sub_f32_e32 v89, v89, v238
	v_sub_f32_e32 v90, v90, v238
	v_sub_f32_e32 v91, v91, v238
	v_sub_f32_e32 v92, v92, v238
	v_sub_f32_e32 v93, v93, v238
	v_sub_f32_e32 v94, v94, v238
	v_sub_f32_e32 v95, v95, v238
.Lmla_skipB:
	v_mfma_f32_32x32x16_bf16 v[48:63], v[234:237], v[120:123], v[48:63]
	ds_read_b128 v[234:237], v220 offset:6688
	s_add_i32 s10, s10, 1
	s_cmp_eq_u32 s10, 3
	s_cselect_b32 s10, 0, s10
	s_add_i32 s9, s9, 1
	s_cmpk_lg_i32 s9, 0x81
	s_cbranch_scc1 .Lmla_loop
	s_waitcnt lgkmcnt(0)
	v_exp_f32_e32 v80, v80
	v_exp_f32_e32 v81, v81
	v_exp_f32_e32 v82, v82
	v_exp_f32_e32 v83, v83
	v_exp_f32_e32 v84, v84
	v_exp_f32_e32 v85, v85
	v_exp_f32_e32 v86, v86
	v_exp_f32_e32 v87, v87
	v_exp_f32_e32 v88, v88
	v_add_f32_e32 v201, v201, v80
	v_exp_f32_e32 v89, v89
	v_add_f32_e32 v201, v201, v81
	v_exp_f32_e32 v90, v90
	v_add_f32_e32 v201, v201, v82
	v_exp_f32_e32 v91, v91
	v_add_f32_e32 v201, v201, v83
	v_exp_f32_e32 v92, v92
	v_add_f32_e32 v201, v201, v84
	v_exp_f32_e32 v93, v93
	v_add_f32_e32 v201, v201, v85
	v_exp_f32_e32 v94, v94
	v_add_f32_e32 v201, v201, v86
	v_exp_f32_e32 v95, v95
	v_add_f32_e32 v201, v201, v87
	v_cvt_pk_bf16_f32 v80, v80, v81
	v_cvt_pk_bf16_f32 v81, v82, v83
	v_cvt_pk_bf16_f32 v82, v84, v85
	v_cvt_pk_bf16_f32 v83, v86, v87
	v_exp_f32_e32 v96, v96
	v_add_f32_e32 v201, v201, v88
	v_exp_f32_e32 v97, v97
	v_add_f32_e32 v201, v201, v89
	v_exp_f32_e32 v98, v98
	v_add_f32_e32 v201, v201, v90
	v_exp_f32_e32 v99, v99
	v_add_f32_e32 v201, v201, v91
	v_exp_f32_e32 v100, v100
	v_add_f32_e32 v201, v201, v92
	v_exp_f32_e32 v101, v101
	v_add_f32_e32 v201, v201, v93
	v_exp_f32_e32 v102, v102
	v_add_f32_e32 v201, v201, v94
	v_exp_f32_e32 v103, v103
	v_add_f32_e32 v201, v201, v95
	v_cvt_pk_bf16_f32 v88, v88, v89
	v_cvt_pk_bf16_f32 v89, v90, v91
	v_cvt_pk_bf16_f32 v90, v92, v93
	v_cvt_pk_bf16_f32 v91, v94, v95
	v_exp_f32_e32 v104, v104
	v_add_f32_e32 v201, v201, v96
	v_exp_f32_e32 v105, v105
	v_add_f32_e32 v201, v201, v97
	v_exp_f32_e32 v106, v106
	v_add_f32_e32 v201, v201, v98
	v_exp_f32_e32 v107, v107
	v_add_f32_e32 v201, v201, v99
	v_exp_f32_e32 v108, v108
	v_add_f32_e32 v201, v201, v100
	v_exp_f32_e32 v109, v109
	v_add_f32_e32 v201, v201, v101
	v_exp_f32_e32 v110, v110
	v_add_f32_e32 v201, v201, v102
	v_exp_f32_e32 v111, v111
	v_add_f32_e32 v201, v201, v103
	v_cvt_pk_bf16_f32 v96, v96, v97
	v_cvt_pk_bf16_f32 v97, v98, v99
	v_cvt_pk_bf16_f32 v98, v100, v101
	v_cvt_pk_bf16_f32 v99, v102, v103
	v_add_f32_e32 v201, v201, v104
	v_add_f32_e32 v201, v201, v105
	v_add_f32_e32 v201, v201, v106
	v_add_f32_e32 v201, v201, v107
	v_add_f32_e32 v201, v201, v108
	v_add_f32_e32 v201, v201, v109
	v_add_f32_e32 v201, v201, v110
	v_add_f32_e32 v201, v201, v111
	v_cvt_pk_bf16_f32 v104, v104, v105
	v_cvt_pk_bf16_f32 v105, v106, v107
	v_cvt_pk_bf16_f32 v106, v108, v109
	v_cvt_pk_bf16_f32 v107, v110, v111
	ds_read_b128 v[222:225], v221 offset:64
	ds_read_b128 v[226:229], v221 offset:4672
	ds_read_b128 v[230:233], v221 offset:96
	ds_read_b128 v[234:237], v221 offset:4704
	s_waitcnt lgkmcnt(3)
	v_mfma_f32_32x32x16_bf16 v[0:15], v[222:225], v[80:83], v[0:15]
	ds_read_b128 v[222:225], v221
	s_waitcnt lgkmcnt(3)
	v_mfma_f32_32x32x16_bf16 v[16:31], v[226:229], v[80:83], v[16:31]
	ds_read_b128 v[226:229], v221 offset:4608
	s_waitcnt lgkmcnt(3)
	v_mfma_f32_32x32x16_bf16 v[0:15], v[230:233], v[88:91], v[0:15]
	ds_read_b128 v[230:233], v221 offset:32
	s_waitcnt lgkmcnt(3)
	v_mfma_f32_32x32x16_bf16 v[16:31], v[234:237], v[88:91], v[16:31]
	ds_read_b128 v[234:237], v221 offset:4640
	s_waitcnt lgkmcnt(3)
	v_mfma_f32_32x32x16_bf16 v[0:15], v[222:225], v[96:99], v[0:15]
	s_waitcnt lgkmcnt(2)
	v_mfma_f32_32x32x16_bf16 v[16:31], v[226:229], v[96:99], v[16:31]
	s_waitcnt lgkmcnt(1)
	v_mfma_f32_32x32x16_bf16 v[0:15], v[230:233], v[104:107], v[0:15]
	s_waitcnt lgkmcnt(0)
	v_mfma_f32_32x32x16_bf16 v[16:31], v[234:237], v[104:107], v[16:31]
	s_barrier
	s_branch .LBB0_216
